# v26 + first-barrier census: 16 counter loads issued back-to-back instead of 15 serial round trips
# speedup vs baseline: 1.0038x; 1.0016x over previous
.LBB0_1182:
	v_readlane_b32 s2, v253, 17
	v_readlane_b32 s3, v253, 18
	global_load_dword v4, v3, s[40:41] sc1
	global_load_dword v2, v3, s[30:31] sc1
	s_mov_b64 s[20:21], -1
	s_nop 2
	global_load_dword v5, v3, s[2:3] sc1
	v_readlane_b32 s2, v253, 19
	v_readlane_b32 s3, v253, 20
	s_nop 4
	global_load_dword v6, v3, s[2:3] sc1
	v_readlane_b32 s2, v253, 21
	v_readlane_b32 s3, v253, 22
	s_nop 4
	global_load_dword v7, v3, s[2:3] sc1
	v_readlane_b32 s2, v253, 23
	v_readlane_b32 s3, v253, 24
	s_nop 4
	global_load_dword v8, v3, s[2:3] sc1
	v_readlane_b32 s2, v253, 25
	v_readlane_b32 s3, v253, 26
	s_nop 4
	global_load_dword v9, v3, s[2:3] sc1
	v_readlane_b32 s2, v253, 27
	v_readlane_b32 s3, v253, 28
	s_nop 4
	global_load_dword v10, v3, s[2:3] sc1
	v_readlane_b32 s2, v253, 29
	v_readlane_b32 s3, v253, 30
	s_nop 4
	global_load_dword v11, v3, s[2:3] sc1
	v_readlane_b32 s2, v253, 31
	v_readlane_b32 s3, v253, 32
	s_nop 4
	global_load_dword v12, v3, s[2:3] sc1
	v_readlane_b32 s2, v253, 33
	v_readlane_b32 s3, v253, 34
	s_nop 4
	global_load_dword v13, v3, s[2:3] sc1
	v_readlane_b32 s2, v253, 35
	v_readlane_b32 s3, v253, 36
	s_nop 4
	global_load_dword v14, v3, s[2:3] sc1
	v_readlane_b32 s2, v253, 37
	v_readlane_b32 s3, v253, 38
	s_nop 4
	global_load_dword v15, v3, s[2:3] sc1
	v_readlane_b32 s2, v253, 39
	v_readlane_b32 s3, v253, 40
	s_nop 4
	global_load_dword v16, v3, s[2:3] sc1
	v_readlane_b32 s2, v253, 41
	v_readlane_b32 s3, v253, 42
	s_nop 4
	global_load_dword v17, v3, s[2:3] sc1
	v_readlane_b32 s2, v253, 43
	v_readlane_b32 s3, v253, 44
	s_nop 4
	global_load_dword v18, v3, s[2:3] sc1
	s_mov_b64 s[2:3], -1
	s_waitcnt vmcnt(0)
	v_add_u32_e32 v19, v2, v4
	v_add_u32_e32 v19, v19, v5
	v_add_u32_e32 v19, v19, v6
	v_add_u32_e32 v19, v19, v7
	v_add_u32_e32 v19, v19, v8
	v_add_u32_e32 v19, v19, v9
	v_add_u32_e32 v19, v19, v10
	v_add_u32_e32 v19, v19, v11
	v_add_u32_e32 v19, v19, v12
	v_add_u32_e32 v19, v19, v13
	v_add_u32_e32 v19, v19, v14
	v_add_u32_e32 v19, v19, v15
	v_add_u32_e32 v19, v19, v16
	v_add_u32_e32 v19, v19, v17
	v_add_u32_e32 v19, v19, v18
	v_cmp_eq_u32_e32 vcc, s4, v19
	s_cbranch_vccnz .LBB0_1181
	s_and_b32 s2, s9, 0xff
	s_cmp_eq_u32 s2, 0
	s_mov_b64 s[2:3], -1
	s_mov_b64 s[22:23], -1
	s_sleep 1
	s_cbranch_scc1 .LBB0_1186
	s_and_b64 vcc, exec, s[22:23]
	s_cbranch_vccz .LBB0_1181
